# rope partner exchange in the in-proj epilogue: ds_bpermute (lane^32) replaced by v_permlane32_swap, on top of packed gelu
# speedup vs baseline: 1.0128x; 1.0013x over previous
.LBB0_252:
	v_mov_b32_e32 v226, v231
	v_mov_b32_e32 v250, v231
	s_nop 1
	v_permlane32_swap_b32_e32 v226, v250
	v_cndmask_b32_e64 v226, v226, v250, s[10:11]
	s_waitcnt lgkmcnt(0)
	v_mul_f32_e32 v226, v149, v226
	v_cndmask_b32_e64 v226, v226, -v226, s[10:11]
	v_fmac_f32_e32 v226, v231, v148
	v_mov_b32_e32 v231, v226

.LBB0_264:
	v_mov_b32_e32 v215, v230
	v_mov_b32_e32 v250, v230
	s_nop 1
	v_permlane32_swap_b32_e32 v215, v250
	v_cndmask_b32_e64 v215, v215, v250, s[10:11]
	s_waitcnt vmcnt(3) lgkmcnt(0)
	v_mul_f32_e32 v215, v149, v215
	v_cndmask_b32_e64 v215, v215, -v215, s[10:11]
	v_fmac_f32_e32 v215, v230, v148
	v_mov_b32_e32 v230, v215

.LBB0_297:
	v_mov_b32_e32 v226, v231
	v_mov_b32_e32 v250, v231
	s_nop 1
	v_permlane32_swap_b32_e32 v226, v250
	v_cndmask_b32_e64 v226, v226, v250, s[10:11]
	s_waitcnt vmcnt(3) lgkmcnt(0)
	v_mul_f32_e32 v226, v137, v226
	v_cndmask_b32_e64 v226, v226, -v226, s[10:11]
	v_fmac_f32_e32 v226, v231, v136
	v_mov_b32_e32 v231, v226

.LBB0_309:
	v_mov_b32_e32 v215, v230
	v_mov_b32_e32 v250, v230
	s_nop 1
	v_permlane32_swap_b32_e32 v215, v250
	v_cndmask_b32_e64 v215, v215, v250, s[10:11]
	s_waitcnt vmcnt(3) lgkmcnt(0)
	v_mul_f32_e32 v215, v137, v215
	v_cndmask_b32_e64 v215, v215, -v215, s[10:11]
	v_fmac_f32_e32 v215, v230, v136
	v_mov_b32_e32 v230, v215

.LBB0_342:
	v_mov_b32_e32 v155, v159
	v_mov_b32_e32 v250, v159
	s_nop 1
	v_permlane32_swap_b32_e32 v155, v250
	v_cndmask_b32_e64 v155, v155, v250, s[10:11]
	s_waitcnt vmcnt(3) lgkmcnt(0)
	v_mul_f32_e32 v155, v121, v155
	v_cndmask_b32_e64 v155, v155, -v155, s[10:11]
	v_fmac_f32_e32 v155, v159, v120
	v_mov_b32_e32 v159, v155

.LBB0_354:
	v_mov_b32_e32 v150, v158
	v_mov_b32_e32 v250, v158
	s_nop 1
	v_permlane32_swap_b32_e32 v150, v250
	v_cndmask_b32_e64 v150, v150, v250, s[10:11]
	s_waitcnt vmcnt(3) lgkmcnt(0)
	v_mul_f32_e32 v150, v121, v150
	v_cndmask_b32_e64 v150, v150, -v150, s[10:11]
	v_fmac_f32_e32 v150, v158, v120
	v_mov_b32_e32 v158, v150

.LBB0_387:
	v_mov_b32_e32 v143, v147
	v_mov_b32_e32 v250, v147
	s_nop 1
	v_permlane32_swap_b32_e32 v143, v250
	v_cndmask_b32_e64 v143, v143, v250, s[10:11]
	s_waitcnt vmcnt(3) lgkmcnt(0)
	v_mul_f32_e32 v143, v105, v143
	v_cndmask_b32_e64 v143, v143, -v143, s[10:11]
	v_fmac_f32_e32 v143, v147, v104
	v_mov_b32_e32 v147, v143

.LBB0_399:
	v_mov_b32_e32 v138, v146
	v_mov_b32_e32 v250, v146
	s_nop 1
	v_permlane32_swap_b32_e32 v138, v250
	v_cndmask_b32_e64 v138, v138, v250, s[10:11]
	s_waitcnt vmcnt(3) lgkmcnt(0)
	v_mul_f32_e32 v138, v105, v138
	v_cndmask_b32_e64 v138, v138, -v138, s[10:11]
	v_fmac_f32_e32 v138, v146, v104
	v_mov_b32_e32 v146, v138

.LBB0_432:
	v_mov_b32_e32 v127, v131
	v_mov_b32_e32 v250, v131
	s_nop 1
	v_permlane32_swap_b32_e32 v127, v250
	v_cndmask_b32_e64 v127, v127, v250, s[10:11]
	s_waitcnt vmcnt(3) lgkmcnt(0)
	v_mul_f32_e32 v127, v89, v127
	v_cndmask_b32_e64 v127, v127, -v127, s[10:11]
	v_fmac_f32_e32 v127, v131, v88
	v_mov_b32_e32 v131, v127

.LBB0_445:
	v_mov_b32_e32 v124, v132
	v_mov_b32_e32 v250, v132
	s_nop 1
	v_permlane32_swap_b32_e32 v124, v250
	v_cndmask_b32_e64 v124, v124, v250, s[10:11]
	s_waitcnt vmcnt(3) lgkmcnt(0)
	v_mul_f32_e32 v124, v89, v124
	v_cndmask_b32_e64 v124, v124, -v124, s[10:11]
	v_fmac_f32_e32 v124, v132, v88
	v_mov_b32_e32 v132, v124

.LBB0_478:
	v_mov_b32_e32 v111, v115
	v_mov_b32_e32 v250, v115
	s_nop 1
	v_permlane32_swap_b32_e32 v111, v250
	v_cndmask_b32_e64 v111, v111, v250, s[10:11]
	s_waitcnt vmcnt(3) lgkmcnt(0)
	v_mul_f32_e32 v111, v73, v111
	v_cndmask_b32_e64 v111, v111, -v111, s[10:11]
	v_fmac_f32_e32 v111, v115, v72
	v_mov_b32_e32 v115, v111

.LBB0_491:
	v_mov_b32_e32 v108, v116
	v_mov_b32_e32 v250, v116
	s_nop 1
	v_permlane32_swap_b32_e32 v108, v250
	v_cndmask_b32_e64 v108, v108, v250, s[10:11]
	s_waitcnt vmcnt(3) lgkmcnt(0)
	v_mul_f32_e32 v108, v73, v108
	v_cndmask_b32_e64 v108, v108, -v108, s[10:11]
	v_fmac_f32_e32 v108, v116, v72
	v_mov_b32_e32 v116, v108

.LBB0_524:
	v_mov_b32_e32 v95, v99
	v_mov_b32_e32 v250, v99
	s_nop 1
	v_permlane32_swap_b32_e32 v95, v250
	v_cndmask_b32_e64 v95, v95, v250, s[10:11]
	s_waitcnt vmcnt(3) lgkmcnt(0)
	v_mul_f32_e32 v95, v57, v95
	v_cndmask_b32_e64 v95, v95, -v95, s[10:11]
	v_fmac_f32_e32 v95, v99, v56
	v_mov_b32_e32 v99, v95

.LBB0_537:
	v_mov_b32_e32 v92, v100
	v_mov_b32_e32 v250, v100
	s_nop 1
	v_permlane32_swap_b32_e32 v92, v250
	v_cndmask_b32_e64 v92, v92, v250, s[10:11]
	s_waitcnt vmcnt(3) lgkmcnt(0)
	v_mul_f32_e32 v92, v57, v92
	v_cndmask_b32_e64 v92, v92, -v92, s[10:11]
	v_fmac_f32_e32 v92, v100, v56
	v_mov_b32_e32 v100, v92

.LBB0_575:
	v_mov_b32_e32 v37, v41
	v_mov_b32_e32 v250, v41
	s_nop 1
	v_permlane32_swap_b32_e32 v37, v250
	v_cndmask_b32_e64 v37, v37, v250, s[10:11]
	s_waitcnt vmcnt(3) lgkmcnt(0)
	v_mul_f32_e32 v37, v57, v37
	v_cndmask_b32_e64 v37, v37, -v37, s[10:11]
	v_fmac_f32_e32 v37, v41, v56
	v_mov_b32_e32 v41, v37

.LBB0_588:
	v_mov_b32_e32 v24, v25
	v_mov_b32_e32 v250, v25
	s_nop 1
	v_permlane32_swap_b32_e32 v24, v250
	v_cndmask_b32_e64 v24, v24, v250, s[10:11]
	s_waitcnt vmcnt(3) lgkmcnt(0)
	v_mul_f32_e32 v24, v57, v24
	v_cndmask_b32_e64 v24, v24, -v24, s[10:11]
	v_fmac_f32_e32 v24, v25, v56
	v_mov_b32_e32 v25, v24

.LBB0_599:
	v_mov_b32_e32 v205, v0
	v_mov_b32_e32 v250, v0
	s_nop 1
	v_permlane32_swap_b32_e32 v205, v250
	v_cndmask_b32_e64 v205, v205, v250, s[10:11]
	s_waitcnt lgkmcnt(0)
	v_mul_f32_e32 v205, v159, v205
	v_cndmask_b32_e64 v205, v205, -v205, s[10:11]
	v_fmac_f32_e32 v205, v0, v158
	v_mov_b32_e32 v0, v205
	v_mul_f32_e32 v205, v163, v216
	s_and_b64 vcc, exec, s[0:1]
	v_mul_f32_e32 v205, v39, v205
	s_cbranch_vccnz .LBB0_246
.LBB0_600:
	v_mov_b32_e32 v206, v205
	v_mov_b32_e32 v250, v205
	s_nop 1
	v_permlane32_swap_b32_e32 v206, v250
	v_cndmask_b32_e64 v206, v206, v250, s[10:11]
	s_waitcnt lgkmcnt(0)
	v_mul_f32_e32 v206, v161, v206
	v_cndmask_b32_e64 v206, v206, -v206, s[10:11]
	v_fmac_f32_e32 v206, v205, v160
	v_mov_b32_e32 v205, v206
	v_mul_f32_e32 v206, v164, v216
	s_and_b64 vcc, exec, s[0:1]
	v_mul_f32_e32 v206, v40, v206
	s_cbranch_vccnz .LBB0_247
.LBB0_601:
	v_mov_b32_e32 v207, v206
	v_mov_b32_e32 v250, v206
	s_nop 1
	v_permlane32_swap_b32_e32 v207, v250
	v_cndmask_b32_e64 v207, v207, v250, s[10:11]
	s_waitcnt lgkmcnt(0)
	v_mul_f32_e32 v207, v155, v207
	v_cndmask_b32_e64 v207, v207, -v207, s[10:11]
	v_fmac_f32_e32 v207, v206, v154
	v_mov_b32_e32 v206, v207
	v_mul_f32_e32 v207, v165, v216
	s_and_b64 vcc, exec, s[0:1]
	v_mul_f32_e32 v207, v41, v207
	s_cbranch_vccnz .LBB0_248
.LBB0_602:
	v_mov_b32_e32 v217, v207
	v_mov_b32_e32 v250, v207
	s_nop 1
	v_permlane32_swap_b32_e32 v217, v250
	v_cndmask_b32_e64 v217, v217, v250, s[10:11]
	s_waitcnt lgkmcnt(0)
	v_mul_f32_e32 v217, v157, v217
	v_cndmask_b32_e64 v217, v217, -v217, s[10:11]
	v_fmac_f32_e32 v217, v207, v156
	v_mov_b32_e32 v207, v217
	v_mul_f32_e32 v217, v142, v216
	s_and_b64 vcc, exec, s[0:1]
	v_mul_f32_e32 v219, v34, v217
	s_cbranch_vccnz .LBB0_249
.LBB0_603:
	v_mov_b32_e32 v217, v219
	v_mov_b32_e32 v250, v219
	s_nop 1
	v_permlane32_swap_b32_e32 v217, v250
	v_cndmask_b32_e64 v217, v217, v250, s[10:11]
	s_waitcnt lgkmcnt(0)
	v_mul_f32_e32 v217, v151, v217
	v_cndmask_b32_e64 v217, v217, -v217, s[10:11]
	v_fmac_f32_e32 v217, v219, v150
	v_mov_b32_e32 v219, v217
	v_mul_f32_e32 v217, v143, v216
	s_and_b64 vcc, exec, s[0:1]
	v_mul_f32_e32 v218, v35, v217
	s_cbranch_vccnz .LBB0_250
.LBB0_604:
	v_mov_b32_e32 v217, v218
	v_mov_b32_e32 v250, v218
	s_nop 1
	v_permlane32_swap_b32_e32 v217, v250
	v_cndmask_b32_e64 v217, v217, v250, s[10:11]
	s_waitcnt lgkmcnt(0)
	v_mul_f32_e32 v217, v153, v217
	v_cndmask_b32_e64 v217, v217, -v217, s[10:11]
	v_fmac_f32_e32 v217, v218, v152
	v_mov_b32_e32 v218, v217
	v_mul_f32_e32 v217, v144, v216
	s_and_b64 vcc, exec, s[0:1]
	v_mul_f32_e32 v217, v36, v217
	s_cbranch_vccnz .LBB0_251
.LBB0_605:
	v_mov_b32_e32 v226, v217
	v_mov_b32_e32 v250, v217
	s_nop 1
	v_permlane32_swap_b32_e32 v226, v250
	v_cndmask_b32_e64 v226, v226, v250, s[10:11]
	s_waitcnt lgkmcnt(0)
	v_mul_f32_e32 v226, v147, v226
	v_cndmask_b32_e64 v226, v226, -v226, s[10:11]
	v_fmac_f32_e32 v226, v217, v146
	v_mov_b32_e32 v217, v226
	v_mul_f32_e32 v226, v145, v216
	s_and_b64 vcc, exec, s[0:1]
	v_mul_f32_e32 v231, v37, v226
	s_cbranch_vccz .LBB0_252
	s_branch .LBB0_253

.LBB0_609:
	v_mov_b32_e32 v217, v0
	v_mov_b32_e32 v250, v0
	s_nop 1
	v_permlane32_swap_b32_e32 v217, v250
	v_cndmask_b32_e64 v217, v217, v250, s[10:11]
	s_waitcnt vmcnt(0) lgkmcnt(0)
	v_mul_f32_e32 v217, v159, v217
	v_cndmask_b32_e64 v217, v217, -v217, s[10:11]
	v_fmac_f32_e32 v217, v0, v158
	v_mov_b32_e32 v0, v217
	v_mul_f32_e32 v217, v139, v216
	s_and_b64 vcc, exec, s[0:1]
	v_mul_f32_e32 v217, v27, v217
	s_cbranch_vccnz .LBB0_258
.LBB0_610:
	v_mov_b32_e32 v218, v217
	v_mov_b32_e32 v250, v217
	s_nop 1
	v_permlane32_swap_b32_e32 v218, v250
	v_cndmask_b32_e64 v218, v218, v250, s[10:11]
	s_waitcnt vmcnt(0) lgkmcnt(0)
	v_mul_f32_e32 v218, v161, v218
	v_cndmask_b32_e64 v218, v218, -v218, s[10:11]
	v_fmac_f32_e32 v218, v217, v160
	v_mov_b32_e32 v217, v218
	v_mul_f32_e32 v218, v140, v216
	s_and_b64 vcc, exec, s[0:1]
	v_mul_f32_e32 v218, v28, v218
	s_cbranch_vccnz .LBB0_259
.LBB0_611:
	v_mov_b32_e32 v219, v218
	v_mov_b32_e32 v250, v218
	s_nop 1
	v_permlane32_swap_b32_e32 v219, v250
	v_cndmask_b32_e64 v219, v219, v250, s[10:11]
	s_waitcnt vmcnt(1) lgkmcnt(0)
	v_mul_f32_e32 v219, v155, v219
	v_cndmask_b32_e64 v219, v219, -v219, s[10:11]
	v_fmac_f32_e32 v219, v218, v154
	v_mov_b32_e32 v218, v219
	v_mul_f32_e32 v219, v141, v216
	s_and_b64 vcc, exec, s[0:1]
	v_mul_f32_e32 v219, v29, v219
	s_cbranch_vccnz .LBB0_260
.LBB0_612:
	v_mov_b32_e32 v226, v219
	v_mov_b32_e32 v250, v219
	s_nop 1
	v_permlane32_swap_b32_e32 v226, v250
	v_cndmask_b32_e64 v226, v226, v250, s[10:11]
	s_waitcnt vmcnt(1) lgkmcnt(0)
	v_mul_f32_e32 v226, v157, v226
	v_cndmask_b32_e64 v226, v226, -v226, s[10:11]
	v_fmac_f32_e32 v226, v219, v156
	v_mov_b32_e32 v219, v226
	v_mul_f32_e32 v226, v134, v216
	s_and_b64 vcc, exec, s[0:1]
	v_mul_f32_e32 v227, v22, v226
	s_cbranch_vccnz .LBB0_261
.LBB0_613:
	v_mov_b32_e32 v226, v227
	v_mov_b32_e32 v250, v227
	s_nop 1
	v_permlane32_swap_b32_e32 v226, v250
	v_cndmask_b32_e64 v226, v226, v250, s[10:11]
	s_waitcnt vmcnt(2) lgkmcnt(0)
	v_mul_f32_e32 v226, v151, v226
	v_cndmask_b32_e64 v226, v226, -v226, s[10:11]
	v_fmac_f32_e32 v226, v227, v150
	v_mov_b32_e32 v227, v226
	v_mul_f32_e32 v226, v135, v216
	s_and_b64 vcc, exec, s[0:1]
	v_mul_f32_e32 v228, v23, v226
	s_cbranch_vccnz .LBB0_262
.LBB0_614:
	v_mov_b32_e32 v226, v228
	v_mov_b32_e32 v250, v228
	s_nop 1
	v_permlane32_swap_b32_e32 v226, v250
	v_cndmask_b32_e64 v226, v226, v250, s[10:11]
	s_waitcnt vmcnt(2) lgkmcnt(0)
	v_mul_f32_e32 v226, v153, v226
	v_cndmask_b32_e64 v226, v226, -v226, s[10:11]
	v_fmac_f32_e32 v226, v228, v152
	v_mov_b32_e32 v228, v226
	v_mul_f32_e32 v226, v136, v216
	s_and_b64 vcc, exec, s[0:1]
	v_mul_f32_e32 v229, v24, v226
	s_cbranch_vccnz .LBB0_263
.LBB0_615:
	v_mov_b32_e32 v226, v229
	v_mov_b32_e32 v250, v229
	s_nop 1
	v_permlane32_swap_b32_e32 v226, v250
	v_cndmask_b32_e64 v226, v226, v250, s[10:11]
	s_waitcnt vmcnt(3) lgkmcnt(0)
	v_mul_f32_e32 v226, v147, v226
	v_cndmask_b32_e64 v226, v226, -v226, s[10:11]
	v_fmac_f32_e32 v226, v229, v146
	v_mov_b32_e32 v229, v226
	v_mul_f32_e32 v216, v137, v216
	s_and_b64 vcc, exec, s[0:1]
	v_mul_f32_e32 v230, v25, v216
	s_cbranch_vccz .LBB0_264
	s_branch .LBB0_265

.LBB0_621:
	v_mov_b32_e32 v205, v0
	v_mov_b32_e32 v250, v0
	s_nop 1
	v_permlane32_swap_b32_e32 v205, v250
	v_cndmask_b32_e64 v205, v205, v250, s[10:11]
	s_waitcnt vmcnt(0) lgkmcnt(0)
	v_mul_f32_e32 v205, v163, v205
	v_cndmask_b32_e64 v205, v205, -v205, s[10:11]
	v_fmac_f32_e32 v205, v0, v162
	v_mov_b32_e32 v0, v205
	v_mul_f32_e32 v205, v131, v216
	s_and_b64 vcc, exec, s[0:1]
	v_mul_f32_e32 v205, v39, v205
	s_cbranch_vccnz .LBB0_291
.LBB0_622:
	v_mov_b32_e32 v206, v205
	v_mov_b32_e32 v250, v205
	s_nop 1
	v_permlane32_swap_b32_e32 v206, v250
	v_cndmask_b32_e64 v206, v206, v250, s[10:11]
	s_waitcnt vmcnt(0) lgkmcnt(0)
	v_mul_f32_e32 v206, v165, v206
	v_cndmask_b32_e64 v206, v206, -v206, s[10:11]
	v_fmac_f32_e32 v206, v205, v164
	v_mov_b32_e32 v205, v206
	v_mul_f32_e32 v206, v132, v216
	s_and_b64 vcc, exec, s[0:1]
	v_mul_f32_e32 v206, v40, v206
	s_cbranch_vccnz .LBB0_292
.LBB0_623:
	v_mov_b32_e32 v207, v206
	v_mov_b32_e32 v250, v206
	s_nop 1
	v_permlane32_swap_b32_e32 v207, v250
	v_cndmask_b32_e64 v207, v207, v250, s[10:11]
	s_waitcnt vmcnt(1) lgkmcnt(0)
	v_mul_f32_e32 v207, v143, v207
	v_cndmask_b32_e64 v207, v207, -v207, s[10:11]
	v_fmac_f32_e32 v207, v206, v142
	v_mov_b32_e32 v206, v207
	v_mul_f32_e32 v207, v133, v216
	s_and_b64 vcc, exec, s[0:1]
	v_mul_f32_e32 v207, v41, v207
	s_cbranch_vccnz .LBB0_293
.LBB0_624:
	v_mov_b32_e32 v217, v207
	v_mov_b32_e32 v250, v207
	s_nop 1
	v_permlane32_swap_b32_e32 v217, v250
	v_cndmask_b32_e64 v217, v217, v250, s[10:11]
	s_waitcnt vmcnt(1) lgkmcnt(0)
	v_mul_f32_e32 v217, v145, v217
	v_cndmask_b32_e64 v217, v217, -v217, s[10:11]
	v_fmac_f32_e32 v217, v207, v144
	v_mov_b32_e32 v207, v217
	v_mul_f32_e32 v217, v126, v216
	s_and_b64 vcc, exec, s[0:1]
	v_mul_f32_e32 v219, v34, v217
	s_cbranch_vccnz .LBB0_294
.LBB0_625:
	v_mov_b32_e32 v217, v219
	v_mov_b32_e32 v250, v219
	s_nop 1
	v_permlane32_swap_b32_e32 v217, v250
	v_cndmask_b32_e64 v217, v217, v250, s[10:11]
	s_waitcnt vmcnt(2) lgkmcnt(0)
	v_mul_f32_e32 v217, v139, v217
	v_cndmask_b32_e64 v217, v217, -v217, s[10:11]
	v_fmac_f32_e32 v217, v219, v138
	v_mov_b32_e32 v219, v217
	v_mul_f32_e32 v217, v127, v216
	s_and_b64 vcc, exec, s[0:1]
	v_mul_f32_e32 v218, v35, v217
	s_cbranch_vccnz .LBB0_295
.LBB0_626:
	v_mov_b32_e32 v217, v218
	v_mov_b32_e32 v250, v218
	s_nop 1
	v_permlane32_swap_b32_e32 v217, v250
	v_cndmask_b32_e64 v217, v217, v250, s[10:11]
	s_waitcnt vmcnt(2) lgkmcnt(0)
	v_mul_f32_e32 v217, v141, v217
	v_cndmask_b32_e64 v217, v217, -v217, s[10:11]
	v_fmac_f32_e32 v217, v218, v140
	v_mov_b32_e32 v218, v217
	v_mul_f32_e32 v217, v128, v216
	s_and_b64 vcc, exec, s[0:1]
	v_mul_f32_e32 v217, v36, v217
	s_cbranch_vccnz .LBB0_296
.LBB0_627:
	v_mov_b32_e32 v226, v217
	v_mov_b32_e32 v250, v217
	s_nop 1
	v_permlane32_swap_b32_e32 v226, v250
	v_cndmask_b32_e64 v226, v226, v250, s[10:11]
	s_waitcnt vmcnt(3) lgkmcnt(0)
	v_mul_f32_e32 v226, v135, v226
	v_cndmask_b32_e64 v226, v226, -v226, s[10:11]
	v_fmac_f32_e32 v226, v217, v134
	v_mov_b32_e32 v217, v226
	v_mul_f32_e32 v226, v129, v216
	s_and_b64 vcc, exec, s[0:1]
	v_mul_f32_e32 v231, v37, v226
	s_cbranch_vccz .LBB0_297
	s_branch .LBB0_298

.LBB0_631:
	v_mov_b32_e32 v217, v0
	v_mov_b32_e32 v250, v0
	s_nop 1
	v_permlane32_swap_b32_e32 v217, v250
	v_cndmask_b32_e64 v217, v217, v250, s[10:11]
	s_waitcnt vmcnt(0) lgkmcnt(0)
	v_mul_f32_e32 v217, v163, v217
	v_cndmask_b32_e64 v217, v217, -v217, s[10:11]
	v_fmac_f32_e32 v217, v0, v162
	v_mov_b32_e32 v0, v217
	v_mul_f32_e32 v217, v123, v216
	s_and_b64 vcc, exec, s[0:1]
	v_mul_f32_e32 v217, v27, v217
	s_cbranch_vccnz .LBB0_303
.LBB0_632:
	v_mov_b32_e32 v218, v217
	v_mov_b32_e32 v250, v217
	s_nop 1
	v_permlane32_swap_b32_e32 v218, v250
	v_cndmask_b32_e64 v218, v218, v250, s[10:11]
	s_waitcnt vmcnt(0) lgkmcnt(0)
	v_mul_f32_e32 v218, v165, v218
	v_cndmask_b32_e64 v218, v218, -v218, s[10:11]
	v_fmac_f32_e32 v218, v217, v164
	v_mov_b32_e32 v217, v218
	v_mul_f32_e32 v218, v124, v216
	s_and_b64 vcc, exec, s[0:1]
	v_mul_f32_e32 v218, v28, v218
	s_cbranch_vccnz .LBB0_304
.LBB0_633:
	v_mov_b32_e32 v219, v218
	v_mov_b32_e32 v250, v218
	s_nop 1
	v_permlane32_swap_b32_e32 v219, v250
	v_cndmask_b32_e64 v219, v219, v250, s[10:11]
	s_waitcnt vmcnt(1) lgkmcnt(0)
	v_mul_f32_e32 v219, v143, v219
	v_cndmask_b32_e64 v219, v219, -v219, s[10:11]
	v_fmac_f32_e32 v219, v218, v142
	v_mov_b32_e32 v218, v219
	v_mul_f32_e32 v219, v125, v216
	s_and_b64 vcc, exec, s[0:1]
	v_mul_f32_e32 v219, v29, v219
	s_cbranch_vccnz .LBB0_305
.LBB0_634:
	v_mov_b32_e32 v226, v219
	v_mov_b32_e32 v250, v219
	s_nop 1
	v_permlane32_swap_b32_e32 v226, v250
	v_cndmask_b32_e64 v226, v226, v250, s[10:11]
	s_waitcnt vmcnt(1) lgkmcnt(0)
	v_mul_f32_e32 v226, v145, v226
	v_cndmask_b32_e64 v226, v226, -v226, s[10:11]
	v_fmac_f32_e32 v226, v219, v144
	v_mov_b32_e32 v219, v226
	v_mul_f32_e32 v226, v118, v216
	s_and_b64 vcc, exec, s[0:1]
	v_mul_f32_e32 v227, v22, v226
	s_cbranch_vccnz .LBB0_306
.LBB0_635:
	v_mov_b32_e32 v226, v227
	v_mov_b32_e32 v250, v227
	s_nop 1
	v_permlane32_swap_b32_e32 v226, v250
	v_cndmask_b32_e64 v226, v226, v250, s[10:11]
	s_waitcnt vmcnt(2) lgkmcnt(0)
	v_mul_f32_e32 v226, v139, v226
	v_cndmask_b32_e64 v226, v226, -v226, s[10:11]
	v_fmac_f32_e32 v226, v227, v138
	v_mov_b32_e32 v227, v226
	v_mul_f32_e32 v226, v119, v216
	s_and_b64 vcc, exec, s[0:1]
	v_mul_f32_e32 v228, v23, v226
	s_cbranch_vccnz .LBB0_307
.LBB0_636:
	v_mov_b32_e32 v226, v228
	v_mov_b32_e32 v250, v228
	s_nop 1
	v_permlane32_swap_b32_e32 v226, v250
	v_cndmask_b32_e64 v226, v226, v250, s[10:11]
	s_waitcnt vmcnt(2) lgkmcnt(0)
	v_mul_f32_e32 v226, v141, v226
	v_cndmask_b32_e64 v226, v226, -v226, s[10:11]
	v_fmac_f32_e32 v226, v228, v140
	v_mov_b32_e32 v228, v226
	v_mul_f32_e32 v226, v120, v216
	s_and_b64 vcc, exec, s[0:1]
	v_mul_f32_e32 v229, v24, v226
	s_cbranch_vccnz .LBB0_308
.LBB0_637:
	v_mov_b32_e32 v226, v229
	v_mov_b32_e32 v250, v229
	s_nop 1
	v_permlane32_swap_b32_e32 v226, v250
	v_cndmask_b32_e64 v226, v226, v250, s[10:11]
	s_waitcnt vmcnt(3) lgkmcnt(0)
	v_mul_f32_e32 v226, v135, v226
	v_cndmask_b32_e64 v226, v226, -v226, s[10:11]
	v_fmac_f32_e32 v226, v229, v134
	v_mov_b32_e32 v229, v226
	v_mul_f32_e32 v216, v121, v216
	s_and_b64 vcc, exec, s[0:1]
	v_mul_f32_e32 v230, v25, v216
	s_cbranch_vccz .LBB0_309
	s_branch .LBB0_310

.LBB0_643:
	v_mov_b32_e32 v147, v0
	v_mov_b32_e32 v250, v0
	s_nop 1
	v_permlane32_swap_b32_e32 v147, v250
	v_cndmask_b32_e64 v147, v147, v250, s[10:11]
	s_waitcnt vmcnt(0) lgkmcnt(0)
	v_mul_f32_e32 v147, v131, v147
	v_cndmask_b32_e64 v147, v147, -v147, s[10:11]
	v_fmac_f32_e32 v147, v0, v130
	v_mov_b32_e32 v0, v147
	v_mul_f32_e32 v147, v115, v151
	s_and_b64 vcc, exec, s[0:1]
	v_mul_f32_e32 v147, v39, v147
	s_cbranch_vccnz .LBB0_336
.LBB0_644:
	v_mov_b32_e32 v148, v147
	v_mov_b32_e32 v250, v147
	s_nop 1
	v_permlane32_swap_b32_e32 v148, v250
	v_cndmask_b32_e64 v148, v148, v250, s[10:11]
	s_waitcnt vmcnt(0) lgkmcnt(0)
	v_mul_f32_e32 v148, v133, v148
	v_cndmask_b32_e64 v148, v148, -v148, s[10:11]
	v_fmac_f32_e32 v148, v147, v132
	v_mov_b32_e32 v147, v148
	v_mul_f32_e32 v148, v116, v151
	s_and_b64 vcc, exec, s[0:1]
	v_mul_f32_e32 v148, v40, v148
	s_cbranch_vccnz .LBB0_337
.LBB0_645:
	v_mov_b32_e32 v149, v148
	v_mov_b32_e32 v250, v148
	s_nop 1
	v_permlane32_swap_b32_e32 v149, v250
	v_cndmask_b32_e64 v149, v149, v250, s[10:11]
	s_waitcnt vmcnt(1) lgkmcnt(0)
	v_mul_f32_e32 v149, v127, v149
	v_cndmask_b32_e64 v149, v149, -v149, s[10:11]
	v_fmac_f32_e32 v149, v148, v126
	v_mov_b32_e32 v148, v149
	v_mul_f32_e32 v149, v117, v151
	s_and_b64 vcc, exec, s[0:1]
	v_mul_f32_e32 v149, v41, v149
	s_cbranch_vccnz .LBB0_338
.LBB0_646:
	v_mov_b32_e32 v152, v149
	v_mov_b32_e32 v250, v149
	s_nop 1
	v_permlane32_swap_b32_e32 v152, v250
	v_cndmask_b32_e64 v152, v152, v250, s[10:11]
	s_waitcnt vmcnt(1) lgkmcnt(0)
	v_mul_f32_e32 v152, v129, v152
	v_cndmask_b32_e64 v152, v152, -v152, s[10:11]
	v_fmac_f32_e32 v152, v149, v128
	v_mov_b32_e32 v149, v152
	v_mul_f32_e32 v152, v110, v151
	s_and_b64 vcc, exec, s[0:1]
	v_mul_f32_e32 v154, v34, v152
	s_cbranch_vccnz .LBB0_339
.LBB0_647:
	v_mov_b32_e32 v152, v154
	v_mov_b32_e32 v250, v154
	s_nop 1
	v_permlane32_swap_b32_e32 v152, v250
	v_cndmask_b32_e64 v152, v152, v250, s[10:11]
	s_waitcnt vmcnt(2) lgkmcnt(0)
	v_mul_f32_e32 v152, v123, v152
	v_cndmask_b32_e64 v152, v152, -v152, s[10:11]
	v_fmac_f32_e32 v152, v154, v122
	v_mov_b32_e32 v154, v152
	v_mul_f32_e32 v152, v111, v151
	s_and_b64 vcc, exec, s[0:1]
	v_mul_f32_e32 v153, v35, v152
	s_cbranch_vccnz .LBB0_340
.LBB0_648:
	v_mov_b32_e32 v152, v153
	v_mov_b32_e32 v250, v153
	s_nop 1
	v_permlane32_swap_b32_e32 v152, v250
	v_cndmask_b32_e64 v152, v152, v250, s[10:11]
	s_waitcnt vmcnt(2) lgkmcnt(0)
	v_mul_f32_e32 v152, v125, v152
	v_cndmask_b32_e64 v152, v152, -v152, s[10:11]
	v_fmac_f32_e32 v152, v153, v124
	v_mov_b32_e32 v153, v152
	v_mul_f32_e32 v152, v112, v151
	s_and_b64 vcc, exec, s[0:1]
	v_mul_f32_e32 v152, v36, v152
	s_cbranch_vccnz .LBB0_341
.LBB0_649:
	v_mov_b32_e32 v155, v152
	v_mov_b32_e32 v250, v152
	s_nop 1
	v_permlane32_swap_b32_e32 v155, v250
	v_cndmask_b32_e64 v155, v155, v250, s[10:11]
	s_waitcnt vmcnt(3) lgkmcnt(0)
	v_mul_f32_e32 v155, v119, v155
	v_cndmask_b32_e64 v155, v155, -v155, s[10:11]
	v_fmac_f32_e32 v155, v152, v118
	v_mov_b32_e32 v152, v155
	v_mul_f32_e32 v155, v113, v151
	s_and_b64 vcc, exec, s[0:1]
	v_mul_f32_e32 v159, v37, v155
	s_cbranch_vccz .LBB0_342
	s_branch .LBB0_343

.LBB0_653:
	v_mov_b32_e32 v152, v0
	v_mov_b32_e32 v250, v0
	s_nop 1
	v_permlane32_swap_b32_e32 v152, v250
	v_cndmask_b32_e64 v152, v152, v250, s[10:11]
	s_waitcnt vmcnt(0) lgkmcnt(0)
	v_mul_f32_e32 v152, v131, v152
	v_cndmask_b32_e64 v152, v152, -v152, s[10:11]
	v_fmac_f32_e32 v152, v0, v130
	v_mov_b32_e32 v0, v152
	v_mul_f32_e32 v152, v107, v151
	s_and_b64 vcc, exec, s[0:1]
	v_mul_f32_e32 v152, v27, v152
	s_cbranch_vccnz .LBB0_348
.LBB0_654:
	v_mov_b32_e32 v153, v152
	v_mov_b32_e32 v250, v152
	s_nop 1
	v_permlane32_swap_b32_e32 v153, v250
	v_cndmask_b32_e64 v153, v153, v250, s[10:11]
	s_waitcnt vmcnt(0) lgkmcnt(0)
	v_mul_f32_e32 v153, v133, v153
	v_cndmask_b32_e64 v153, v153, -v153, s[10:11]
	v_fmac_f32_e32 v153, v152, v132
	v_mov_b32_e32 v152, v153
	v_mul_f32_e32 v153, v108, v151
	s_and_b64 vcc, exec, s[0:1]
	v_mul_f32_e32 v153, v28, v153
	s_cbranch_vccnz .LBB0_349
.LBB0_655:
	v_mov_b32_e32 v154, v153
	v_mov_b32_e32 v250, v153
	s_nop 1
	v_permlane32_swap_b32_e32 v154, v250
	v_cndmask_b32_e64 v154, v154, v250, s[10:11]
	s_waitcnt vmcnt(1) lgkmcnt(0)
	v_mul_f32_e32 v154, v127, v154
	v_cndmask_b32_e64 v154, v154, -v154, s[10:11]
	v_fmac_f32_e32 v154, v153, v126
	v_mov_b32_e32 v153, v154
	v_mul_f32_e32 v154, v109, v151
	s_and_b64 vcc, exec, s[0:1]
	v_mul_f32_e32 v154, v29, v154
	s_cbranch_vccnz .LBB0_350
.LBB0_656:
	v_mov_b32_e32 v155, v154
	v_mov_b32_e32 v250, v154
	s_nop 1
	v_permlane32_swap_b32_e32 v155, v250
	v_cndmask_b32_e64 v155, v155, v250, s[10:11]
	s_waitcnt vmcnt(1) lgkmcnt(0)
	v_mul_f32_e32 v155, v129, v155
	v_cndmask_b32_e64 v155, v155, -v155, s[10:11]
	v_fmac_f32_e32 v155, v154, v128
	v_mov_b32_e32 v154, v155
	v_mul_f32_e32 v155, v102, v151
	s_and_b64 vcc, exec, s[0:1]
	v_mul_f32_e32 v155, v22, v155
	s_cbranch_vccnz .LBB0_351
.LBB0_657:
	v_mov_b32_e32 v156, v155
	v_mov_b32_e32 v250, v155
	s_nop 1
	v_permlane32_swap_b32_e32 v156, v250
	v_cndmask_b32_e64 v156, v156, v250, s[10:11]
	s_waitcnt vmcnt(2) lgkmcnt(0)
	v_mul_f32_e32 v156, v123, v156
	v_cndmask_b32_e64 v156, v156, -v156, s[10:11]
	v_fmac_f32_e32 v156, v155, v122
	v_mov_b32_e32 v155, v156
	v_mul_f32_e32 v156, v103, v151
	s_and_b64 vcc, exec, s[0:1]
	v_mul_f32_e32 v156, v23, v156
	s_cbranch_vccnz .LBB0_352
.LBB0_658:
	v_mov_b32_e32 v157, v156
	v_mov_b32_e32 v250, v156
	s_nop 1
	v_permlane32_swap_b32_e32 v157, v250
	v_cndmask_b32_e64 v157, v157, v250, s[10:11]
	s_waitcnt vmcnt(2) lgkmcnt(0)
	v_mul_f32_e32 v157, v125, v157
	v_cndmask_b32_e64 v157, v157, -v157, s[10:11]
	v_fmac_f32_e32 v157, v156, v124
	v_mov_b32_e32 v156, v157
	v_mul_f32_e32 v157, v104, v151
	s_and_b64 vcc, exec, s[0:1]
	v_mul_f32_e32 v157, v24, v157
	s_cbranch_vccnz .LBB0_353
.LBB0_659:
	v_mov_b32_e32 v158, v157
	v_mov_b32_e32 v250, v157
	s_nop 1
	v_permlane32_swap_b32_e32 v158, v250
	v_cndmask_b32_e64 v158, v158, v250, s[10:11]
	s_waitcnt vmcnt(3) lgkmcnt(0)
	v_mul_f32_e32 v158, v119, v158
	v_cndmask_b32_e64 v158, v158, -v158, s[10:11]
	v_fmac_f32_e32 v158, v157, v118
	v_mov_b32_e32 v157, v158
	v_mul_f32_e32 v151, v105, v151
	s_and_b64 vcc, exec, s[0:1]
	v_mul_f32_e32 v158, v25, v151
	s_cbranch_vccz .LBB0_354
	s_branch .LBB0_355

.LBB0_665:
	v_mov_b32_e32 v135, v0
	v_mov_b32_e32 v250, v0
	s_nop 1
	v_permlane32_swap_b32_e32 v135, v250
	v_cndmask_b32_e64 v135, v135, v250, s[10:11]
	s_waitcnt vmcnt(0) lgkmcnt(0)
	v_mul_f32_e32 v135, v115, v135
	v_cndmask_b32_e64 v135, v135, -v135, s[10:11]
	v_fmac_f32_e32 v135, v0, v114
	v_mov_b32_e32 v0, v135
	v_mul_f32_e32 v135, v99, v139
	s_and_b64 vcc, exec, s[0:1]
	v_mul_f32_e32 v135, v39, v135
	s_cbranch_vccnz .LBB0_381
.LBB0_666:
	v_mov_b32_e32 v136, v135
	v_mov_b32_e32 v250, v135
	s_nop 1
	v_permlane32_swap_b32_e32 v136, v250
	v_cndmask_b32_e64 v136, v136, v250, s[10:11]
	s_waitcnt vmcnt(0) lgkmcnt(0)
	v_mul_f32_e32 v136, v117, v136
	v_cndmask_b32_e64 v136, v136, -v136, s[10:11]
	v_fmac_f32_e32 v136, v135, v116
	v_mov_b32_e32 v135, v136
	v_mul_f32_e32 v136, v100, v139
	s_and_b64 vcc, exec, s[0:1]
	v_mul_f32_e32 v136, v40, v136
	s_cbranch_vccnz .LBB0_382
.LBB0_667:
	v_mov_b32_e32 v137, v136
	v_mov_b32_e32 v250, v136
	s_nop 1
	v_permlane32_swap_b32_e32 v137, v250
	v_cndmask_b32_e64 v137, v137, v250, s[10:11]
	s_waitcnt vmcnt(1) lgkmcnt(0)
	v_mul_f32_e32 v137, v111, v137
	v_cndmask_b32_e64 v137, v137, -v137, s[10:11]
	v_fmac_f32_e32 v137, v136, v110
	v_mov_b32_e32 v136, v137
	v_mul_f32_e32 v137, v101, v139
	s_and_b64 vcc, exec, s[0:1]
	v_mul_f32_e32 v137, v41, v137
	s_cbranch_vccnz .LBB0_383
.LBB0_668:
	v_mov_b32_e32 v140, v137
	v_mov_b32_e32 v250, v137
	s_nop 1
	v_permlane32_swap_b32_e32 v140, v250
	v_cndmask_b32_e64 v140, v140, v250, s[10:11]
	s_waitcnt vmcnt(1) lgkmcnt(0)
	v_mul_f32_e32 v140, v113, v140
	v_cndmask_b32_e64 v140, v140, -v140, s[10:11]
	v_fmac_f32_e32 v140, v137, v112
	v_mov_b32_e32 v137, v140
	v_mul_f32_e32 v140, v94, v139
	s_and_b64 vcc, exec, s[0:1]
	v_mul_f32_e32 v142, v34, v140
	s_cbranch_vccnz .LBB0_384
.LBB0_669:
	v_mov_b32_e32 v140, v142
	v_mov_b32_e32 v250, v142
	s_nop 1
	v_permlane32_swap_b32_e32 v140, v250
	v_cndmask_b32_e64 v140, v140, v250, s[10:11]
	s_waitcnt vmcnt(2) lgkmcnt(0)
	v_mul_f32_e32 v140, v107, v140
	v_cndmask_b32_e64 v140, v140, -v140, s[10:11]
	v_fmac_f32_e32 v140, v142, v106
	v_mov_b32_e32 v142, v140
	v_mul_f32_e32 v140, v95, v139
	s_and_b64 vcc, exec, s[0:1]
	v_mul_f32_e32 v141, v35, v140
	s_cbranch_vccnz .LBB0_385
.LBB0_670:
	v_mov_b32_e32 v140, v141
	v_mov_b32_e32 v250, v141
	s_nop 1
	v_permlane32_swap_b32_e32 v140, v250
	v_cndmask_b32_e64 v140, v140, v250, s[10:11]
	s_waitcnt vmcnt(2) lgkmcnt(0)
	v_mul_f32_e32 v140, v109, v140
	v_cndmask_b32_e64 v140, v140, -v140, s[10:11]
	v_fmac_f32_e32 v140, v141, v108
	v_mov_b32_e32 v141, v140
	v_mul_f32_e32 v140, v96, v139
	s_and_b64 vcc, exec, s[0:1]
	v_mul_f32_e32 v140, v36, v140
	s_cbranch_vccnz .LBB0_386
.LBB0_671:
	v_mov_b32_e32 v143, v140
	v_mov_b32_e32 v250, v140
	s_nop 1
	v_permlane32_swap_b32_e32 v143, v250
	v_cndmask_b32_e64 v143, v143, v250, s[10:11]
	s_waitcnt vmcnt(3) lgkmcnt(0)
	v_mul_f32_e32 v143, v103, v143
	v_cndmask_b32_e64 v143, v143, -v143, s[10:11]
	v_fmac_f32_e32 v143, v140, v102
	v_mov_b32_e32 v140, v143
	v_mul_f32_e32 v143, v97, v139
	s_and_b64 vcc, exec, s[0:1]
	v_mul_f32_e32 v147, v37, v143
	s_cbranch_vccz .LBB0_387
	s_branch .LBB0_388

.LBB0_675:
	v_mov_b32_e32 v140, v0
	v_mov_b32_e32 v250, v0
	s_nop 1
	v_permlane32_swap_b32_e32 v140, v250
	v_cndmask_b32_e64 v140, v140, v250, s[10:11]
	s_waitcnt vmcnt(0) lgkmcnt(0)
	v_mul_f32_e32 v140, v115, v140
	v_cndmask_b32_e64 v140, v140, -v140, s[10:11]
	v_fmac_f32_e32 v140, v0, v114
	v_mov_b32_e32 v0, v140
	v_mul_f32_e32 v140, v91, v139
	s_and_b64 vcc, exec, s[0:1]
	v_mul_f32_e32 v140, v27, v140
	s_cbranch_vccnz .LBB0_393
.LBB0_676:
	v_mov_b32_e32 v141, v140
	v_mov_b32_e32 v250, v140
	s_nop 1
	v_permlane32_swap_b32_e32 v141, v250
	v_cndmask_b32_e64 v141, v141, v250, s[10:11]
	s_waitcnt vmcnt(0) lgkmcnt(0)
	v_mul_f32_e32 v141, v117, v141
	v_cndmask_b32_e64 v141, v141, -v141, s[10:11]
	v_fmac_f32_e32 v141, v140, v116
	v_mov_b32_e32 v140, v141
	v_mul_f32_e32 v141, v92, v139
	s_and_b64 vcc, exec, s[0:1]
	v_mul_f32_e32 v141, v28, v141
	s_cbranch_vccnz .LBB0_394
.LBB0_677:
	v_mov_b32_e32 v142, v141
	v_mov_b32_e32 v250, v141
	s_nop 1
	v_permlane32_swap_b32_e32 v142, v250
	v_cndmask_b32_e64 v142, v142, v250, s[10:11]
	s_waitcnt vmcnt(1) lgkmcnt(0)
	v_mul_f32_e32 v142, v111, v142
	v_cndmask_b32_e64 v142, v142, -v142, s[10:11]
	v_fmac_f32_e32 v142, v141, v110
	v_mov_b32_e32 v141, v142
	v_mul_f32_e32 v142, v93, v139
	s_and_b64 vcc, exec, s[0:1]
	v_mul_f32_e32 v142, v29, v142
	s_cbranch_vccnz .LBB0_395
.LBB0_678:
	v_mov_b32_e32 v143, v142
	v_mov_b32_e32 v250, v142
	s_nop 1
	v_permlane32_swap_b32_e32 v143, v250
	v_cndmask_b32_e64 v143, v143, v250, s[10:11]
	s_waitcnt vmcnt(1) lgkmcnt(0)
	v_mul_f32_e32 v143, v113, v143
	v_cndmask_b32_e64 v143, v143, -v143, s[10:11]
	v_fmac_f32_e32 v143, v142, v112
	v_mov_b32_e32 v142, v143
	v_mul_f32_e32 v143, v86, v139
	s_and_b64 vcc, exec, s[0:1]
	v_mul_f32_e32 v143, v22, v143
	s_cbranch_vccnz .LBB0_396
.LBB0_679:
	v_mov_b32_e32 v144, v143
	v_mov_b32_e32 v250, v143
	s_nop 1
	v_permlane32_swap_b32_e32 v144, v250
	v_cndmask_b32_e64 v144, v144, v250, s[10:11]
	s_waitcnt vmcnt(2) lgkmcnt(0)
	v_mul_f32_e32 v144, v107, v144
	v_cndmask_b32_e64 v144, v144, -v144, s[10:11]
	v_fmac_f32_e32 v144, v143, v106
	v_mov_b32_e32 v143, v144
	v_mul_f32_e32 v144, v87, v139
	s_and_b64 vcc, exec, s[0:1]
	v_mul_f32_e32 v144, v23, v144
	s_cbranch_vccnz .LBB0_397
.LBB0_680:
	v_mov_b32_e32 v145, v144
	v_mov_b32_e32 v250, v144
	s_nop 1
	v_permlane32_swap_b32_e32 v145, v250
	v_cndmask_b32_e64 v145, v145, v250, s[10:11]
	s_waitcnt vmcnt(2) lgkmcnt(0)
	v_mul_f32_e32 v145, v109, v145
	v_cndmask_b32_e64 v145, v145, -v145, s[10:11]
	v_fmac_f32_e32 v145, v144, v108
	v_mov_b32_e32 v144, v145
	v_mul_f32_e32 v145, v88, v139
	s_and_b64 vcc, exec, s[0:1]
	v_mul_f32_e32 v145, v24, v145
	s_cbranch_vccnz .LBB0_398
.LBB0_681:
	v_mov_b32_e32 v146, v145
	v_mov_b32_e32 v250, v145
	s_nop 1
	v_permlane32_swap_b32_e32 v146, v250
	v_cndmask_b32_e64 v146, v146, v250, s[10:11]
	s_waitcnt vmcnt(3) lgkmcnt(0)
	v_mul_f32_e32 v146, v103, v146
	v_cndmask_b32_e64 v146, v146, -v146, s[10:11]
	v_fmac_f32_e32 v146, v145, v102
	v_mov_b32_e32 v145, v146
	v_mul_f32_e32 v139, v89, v139
	s_and_b64 vcc, exec, s[0:1]
	v_mul_f32_e32 v146, v25, v139
	s_cbranch_vccz .LBB0_399
	s_branch .LBB0_400

.LBB0_687:
	v_mov_b32_e32 v119, v0
	v_mov_b32_e32 v250, v0
	s_nop 1
	v_permlane32_swap_b32_e32 v119, v250
	v_cndmask_b32_e64 v119, v119, v250, s[10:11]
	s_waitcnt vmcnt(0) lgkmcnt(0)
	v_mul_f32_e32 v119, v99, v119
	v_cndmask_b32_e64 v119, v119, -v119, s[10:11]
	v_fmac_f32_e32 v119, v0, v98
	v_mov_b32_e32 v0, v119
	v_mul_f32_e32 v119, v83, v125
	s_and_b64 vcc, exec, s[0:1]
	v_mul_f32_e32 v119, v39, v119
	s_cbranch_vccnz .LBB0_426
.LBB0_688:
	v_mov_b32_e32 v120, v119
	v_mov_b32_e32 v250, v119
	s_nop 1
	v_permlane32_swap_b32_e32 v120, v250
	v_cndmask_b32_e64 v120, v120, v250, s[10:11]
	s_waitcnt vmcnt(0) lgkmcnt(0)
	v_mul_f32_e32 v120, v101, v120
	v_cndmask_b32_e64 v120, v120, -v120, s[10:11]
	v_fmac_f32_e32 v120, v119, v100
	v_mov_b32_e32 v119, v120
	v_mul_f32_e32 v120, v84, v125
	s_and_b64 vcc, exec, s[0:1]
	v_mul_f32_e32 v120, v40, v120
	s_cbranch_vccnz .LBB0_427
.LBB0_689:
	v_mov_b32_e32 v121, v120
	v_mov_b32_e32 v250, v120
	s_nop 1
	v_permlane32_swap_b32_e32 v121, v250
	v_cndmask_b32_e64 v121, v121, v250, s[10:11]
	s_waitcnt vmcnt(1) lgkmcnt(0)
	v_mul_f32_e32 v121, v95, v121
	v_cndmask_b32_e64 v121, v121, -v121, s[10:11]
	v_fmac_f32_e32 v121, v120, v94
	v_mov_b32_e32 v120, v121
	v_mul_f32_e32 v121, v85, v125
	s_and_b64 vcc, exec, s[0:1]
	v_mul_f32_e32 v121, v41, v121
	s_cbranch_vccnz .LBB0_428
.LBB0_690:
	v_mov_b32_e32 v122, v121
	v_mov_b32_e32 v250, v121
	s_nop 1
	v_permlane32_swap_b32_e32 v122, v250
	v_cndmask_b32_e64 v122, v122, v250, s[10:11]
	s_waitcnt vmcnt(1) lgkmcnt(0)
	v_mul_f32_e32 v122, v97, v122
	v_cndmask_b32_e64 v122, v122, -v122, s[10:11]
	v_fmac_f32_e32 v122, v121, v96
	v_mov_b32_e32 v121, v122
	v_mul_f32_e32 v122, v78, v125
	s_and_b64 vcc, exec, s[0:1]
	v_mul_f32_e32 v122, v34, v122
	s_cbranch_vccnz .LBB0_429
.LBB0_691:
	v_mov_b32_e32 v123, v122
	v_mov_b32_e32 v250, v122
	s_nop 1
	v_permlane32_swap_b32_e32 v123, v250
	v_cndmask_b32_e64 v123, v123, v250, s[10:11]
	s_waitcnt vmcnt(2) lgkmcnt(0)
	v_mul_f32_e32 v123, v91, v123
	v_cndmask_b32_e64 v123, v123, -v123, s[10:11]
	v_fmac_f32_e32 v123, v122, v90
	v_mov_b32_e32 v122, v123
	v_mul_f32_e32 v123, v79, v125
	s_and_b64 vcc, exec, s[0:1]
	v_mul_f32_e32 v123, v35, v123
	s_cbranch_vccnz .LBB0_430
.LBB0_692:
	v_mov_b32_e32 v126, v123
	v_mov_b32_e32 v250, v123
	s_nop 1
	v_permlane32_swap_b32_e32 v126, v250
	v_cndmask_b32_e64 v126, v126, v250, s[10:11]
	s_waitcnt vmcnt(2) lgkmcnt(0)
	v_mul_f32_e32 v126, v93, v126
	v_cndmask_b32_e64 v126, v126, -v126, s[10:11]
	v_fmac_f32_e32 v126, v123, v92
	v_mov_b32_e32 v123, v126
	v_mul_f32_e32 v126, v80, v125
	s_and_b64 vcc, exec, s[0:1]
	v_mul_f32_e32 v126, v36, v126
	s_cbranch_vccnz .LBB0_431
.LBB0_693:
	v_mov_b32_e32 v127, v126
	v_mov_b32_e32 v250, v126
	s_nop 1
	v_permlane32_swap_b32_e32 v127, v250
	v_cndmask_b32_e64 v127, v127, v250, s[10:11]
	s_waitcnt vmcnt(3) lgkmcnt(0)
	v_mul_f32_e32 v127, v87, v127
	v_cndmask_b32_e64 v127, v127, -v127, s[10:11]
	v_fmac_f32_e32 v127, v126, v86
	v_mov_b32_e32 v126, v127
	v_mul_f32_e32 v127, v81, v125
	s_and_b64 vcc, exec, s[0:1]
	v_mul_f32_e32 v131, v37, v127
	s_cbranch_vccz .LBB0_432
	s_branch .LBB0_433

.LBB0_696:
	v_mov_b32_e32 v122, v0
	v_mov_b32_e32 v250, v0
	s_nop 1
	v_permlane32_swap_b32_e32 v122, v250
	v_cndmask_b32_e64 v122, v122, v250, s[10:11]
	s_waitcnt vmcnt(0) lgkmcnt(0)
	v_mul_f32_e32 v122, v99, v122
	v_cndmask_b32_e64 v122, v122, -v122, s[10:11]
	v_fmac_f32_e32 v122, v0, v98
	v_mov_b32_e32 v0, v122
	v_mul_f32_e32 v122, v75, v125
	s_and_b64 vcc, exec, s[0:1]
	v_mul_f32_e32 v122, v27, v122
	s_cbranch_vccnz .LBB0_439
.LBB0_697:
	v_mov_b32_e32 v126, v122
	v_mov_b32_e32 v250, v122
	s_nop 1
	v_permlane32_swap_b32_e32 v126, v250
	v_cndmask_b32_e64 v126, v126, v250, s[10:11]
	s_waitcnt vmcnt(0) lgkmcnt(0)
	v_mul_f32_e32 v126, v101, v126
	v_cndmask_b32_e64 v126, v126, -v126, s[10:11]
	v_fmac_f32_e32 v126, v122, v100
	v_mov_b32_e32 v122, v126
	v_mul_f32_e32 v126, v76, v125
	s_and_b64 vcc, exec, s[0:1]
	v_mul_f32_e32 v126, v28, v126
	s_cbranch_vccnz .LBB0_440
.LBB0_698:
	v_mov_b32_e32 v127, v126
	v_mov_b32_e32 v250, v126
	s_nop 1
	v_permlane32_swap_b32_e32 v127, v250
	v_cndmask_b32_e64 v127, v127, v250, s[10:11]
	s_waitcnt vmcnt(1) lgkmcnt(0)
	v_mul_f32_e32 v127, v95, v127
	v_cndmask_b32_e64 v127, v127, -v127, s[10:11]
	v_fmac_f32_e32 v127, v126, v94
	v_mov_b32_e32 v126, v127
	v_mul_f32_e32 v127, v77, v125
	s_and_b64 vcc, exec, s[0:1]
	v_mul_f32_e32 v127, v29, v127
	s_cbranch_vccnz .LBB0_441
.LBB0_699:
	v_mov_b32_e32 v128, v127
	v_mov_b32_e32 v250, v127
	s_nop 1
	v_permlane32_swap_b32_e32 v128, v250
	v_cndmask_b32_e64 v128, v128, v250, s[10:11]
	s_waitcnt vmcnt(1) lgkmcnt(0)
	v_mul_f32_e32 v128, v97, v128
	v_cndmask_b32_e64 v128, v128, -v128, s[10:11]
	v_fmac_f32_e32 v128, v127, v96
	v_mov_b32_e32 v127, v128
	v_mul_f32_e32 v128, v70, v125
	s_and_b64 vcc, exec, s[0:1]
	v_mul_f32_e32 v128, v22, v128
	s_cbranch_vccnz .LBB0_442
.LBB0_700:
	v_mov_b32_e32 v129, v128
	v_mov_b32_e32 v250, v128
	s_nop 1
	v_permlane32_swap_b32_e32 v129, v250
	v_cndmask_b32_e64 v129, v129, v250, s[10:11]
	s_waitcnt vmcnt(2) lgkmcnt(0)
	v_mul_f32_e32 v129, v91, v129
	v_cndmask_b32_e64 v129, v129, -v129, s[10:11]
	v_fmac_f32_e32 v129, v128, v90
	v_mov_b32_e32 v128, v129
	v_mul_f32_e32 v129, v71, v125
	s_and_b64 vcc, exec, s[0:1]
	v_mul_f32_e32 v129, v23, v129
	s_cbranch_vccnz .LBB0_443
.LBB0_701:
	v_mov_b32_e32 v130, v129
	v_mov_b32_e32 v250, v129
	s_nop 1
	v_permlane32_swap_b32_e32 v130, v250
	v_cndmask_b32_e64 v130, v130, v250, s[10:11]
	s_waitcnt vmcnt(2) lgkmcnt(0)
	v_mul_f32_e32 v130, v93, v130
	v_cndmask_b32_e64 v130, v130, -v130, s[10:11]
	v_fmac_f32_e32 v130, v129, v92
	v_mov_b32_e32 v129, v130
	v_mul_f32_e32 v130, v72, v125
	s_and_b64 vcc, exec, s[0:1]
	v_mul_f32_e32 v130, v24, v130
	s_cbranch_vccnz .LBB0_444
.LBB0_702:
	v_mov_b32_e32 v131, v130
	v_mov_b32_e32 v250, v130
	s_nop 1
	v_permlane32_swap_b32_e32 v131, v250
	v_cndmask_b32_e64 v131, v131, v250, s[10:11]
	s_waitcnt vmcnt(3) lgkmcnt(0)
	v_mul_f32_e32 v131, v87, v131
	v_cndmask_b32_e64 v131, v131, -v131, s[10:11]
	v_fmac_f32_e32 v131, v130, v86
	v_mov_b32_e32 v130, v131
	v_mul_f32_e32 v125, v73, v125
	s_and_b64 vcc, exec, s[0:1]
	v_mul_f32_e32 v132, v25, v125
	s_cbranch_vccz .LBB0_445
	s_branch .LBB0_446

.LBB0_708:
	v_mov_b32_e32 v103, v0
	v_mov_b32_e32 v250, v0
	s_nop 1
	v_permlane32_swap_b32_e32 v103, v250
	v_cndmask_b32_e64 v103, v103, v250, s[10:11]
	s_waitcnt vmcnt(0) lgkmcnt(0)
	v_mul_f32_e32 v103, v83, v103
	v_cndmask_b32_e64 v103, v103, -v103, s[10:11]
	v_fmac_f32_e32 v103, v0, v82
	v_mov_b32_e32 v0, v103
	v_mul_f32_e32 v103, v67, v109
	s_and_b64 vcc, exec, s[0:1]
	v_mul_f32_e32 v103, v39, v103
	s_cbranch_vccnz .LBB0_472
.LBB0_709:
	v_mov_b32_e32 v104, v103
	v_mov_b32_e32 v250, v103
	s_nop 1
	v_permlane32_swap_b32_e32 v104, v250
	v_cndmask_b32_e64 v104, v104, v250, s[10:11]
	s_waitcnt vmcnt(0) lgkmcnt(0)
	v_mul_f32_e32 v104, v85, v104
	v_cndmask_b32_e64 v104, v104, -v104, s[10:11]
	v_fmac_f32_e32 v104, v103, v84
	v_mov_b32_e32 v103, v104
	v_mul_f32_e32 v104, v68, v109
	s_and_b64 vcc, exec, s[0:1]
	v_mul_f32_e32 v104, v40, v104
	s_cbranch_vccnz .LBB0_473
.LBB0_710:
	v_mov_b32_e32 v105, v104
	v_mov_b32_e32 v250, v104
	s_nop 1
	v_permlane32_swap_b32_e32 v105, v250
	v_cndmask_b32_e64 v105, v105, v250, s[10:11]
	s_waitcnt vmcnt(1) lgkmcnt(0)
	v_mul_f32_e32 v105, v79, v105
	v_cndmask_b32_e64 v105, v105, -v105, s[10:11]
	v_fmac_f32_e32 v105, v104, v78
	v_mov_b32_e32 v104, v105
	v_mul_f32_e32 v105, v69, v109
	s_and_b64 vcc, exec, s[0:1]
	v_mul_f32_e32 v105, v41, v105
	s_cbranch_vccnz .LBB0_474
.LBB0_711:
	v_mov_b32_e32 v106, v105
	v_mov_b32_e32 v250, v105
	s_nop 1
	v_permlane32_swap_b32_e32 v106, v250
	v_cndmask_b32_e64 v106, v106, v250, s[10:11]
	s_waitcnt vmcnt(1) lgkmcnt(0)
	v_mul_f32_e32 v106, v81, v106
	v_cndmask_b32_e64 v106, v106, -v106, s[10:11]
	v_fmac_f32_e32 v106, v105, v80
	v_mov_b32_e32 v105, v106
	v_mul_f32_e32 v106, v62, v109
	s_and_b64 vcc, exec, s[0:1]
	v_mul_f32_e32 v106, v34, v106
	s_cbranch_vccnz .LBB0_475
.LBB0_712:
	v_mov_b32_e32 v107, v106
	v_mov_b32_e32 v250, v106
	s_nop 1
	v_permlane32_swap_b32_e32 v107, v250
	v_cndmask_b32_e64 v107, v107, v250, s[10:11]
	s_waitcnt vmcnt(2) lgkmcnt(0)
	v_mul_f32_e32 v107, v75, v107
	v_cndmask_b32_e64 v107, v107, -v107, s[10:11]
	v_fmac_f32_e32 v107, v106, v74
	v_mov_b32_e32 v106, v107
	v_mul_f32_e32 v107, v63, v109
	s_and_b64 vcc, exec, s[0:1]
	v_mul_f32_e32 v107, v35, v107
	s_cbranch_vccnz .LBB0_476
.LBB0_713:
	v_mov_b32_e32 v110, v107
	v_mov_b32_e32 v250, v107
	s_nop 1
	v_permlane32_swap_b32_e32 v110, v250
	v_cndmask_b32_e64 v110, v110, v250, s[10:11]
	s_waitcnt vmcnt(2) lgkmcnt(0)
	v_mul_f32_e32 v110, v77, v110
	v_cndmask_b32_e64 v110, v110, -v110, s[10:11]
	v_fmac_f32_e32 v110, v107, v76
	v_mov_b32_e32 v107, v110
	v_mul_f32_e32 v110, v64, v109
	s_and_b64 vcc, exec, s[0:1]
	v_mul_f32_e32 v110, v36, v110
	s_cbranch_vccnz .LBB0_477
.LBB0_714:
	v_mov_b32_e32 v111, v110
	v_mov_b32_e32 v250, v110
	s_nop 1
	v_permlane32_swap_b32_e32 v111, v250
	v_cndmask_b32_e64 v111, v111, v250, s[10:11]
	s_waitcnt vmcnt(3) lgkmcnt(0)
	v_mul_f32_e32 v111, v71, v111
	v_cndmask_b32_e64 v111, v111, -v111, s[10:11]
	v_fmac_f32_e32 v111, v110, v70
	v_mov_b32_e32 v110, v111
	v_mul_f32_e32 v111, v65, v109
	s_and_b64 vcc, exec, s[0:1]
	v_mul_f32_e32 v115, v37, v111
	s_cbranch_vccz .LBB0_478
	s_branch .LBB0_479

.LBB0_717:
	v_mov_b32_e32 v106, v0
	v_mov_b32_e32 v250, v0
	s_nop 1
	v_permlane32_swap_b32_e32 v106, v250
	v_cndmask_b32_e64 v106, v106, v250, s[10:11]
	s_waitcnt vmcnt(0) lgkmcnt(0)
	v_mul_f32_e32 v106, v83, v106
	v_cndmask_b32_e64 v106, v106, -v106, s[10:11]
	v_fmac_f32_e32 v106, v0, v82
	v_mov_b32_e32 v0, v106
	v_mul_f32_e32 v106, v59, v109
	s_and_b64 vcc, exec, s[0:1]
	v_mul_f32_e32 v106, v27, v106
	s_cbranch_vccnz .LBB0_485
.LBB0_718:
	v_mov_b32_e32 v110, v106
	v_mov_b32_e32 v250, v106
	s_nop 1
	v_permlane32_swap_b32_e32 v110, v250
	v_cndmask_b32_e64 v110, v110, v250, s[10:11]
	s_waitcnt vmcnt(0) lgkmcnt(0)
	v_mul_f32_e32 v110, v85, v110
	v_cndmask_b32_e64 v110, v110, -v110, s[10:11]
	v_fmac_f32_e32 v110, v106, v84
	v_mov_b32_e32 v106, v110
	v_mul_f32_e32 v110, v60, v109
	s_and_b64 vcc, exec, s[0:1]
	v_mul_f32_e32 v110, v28, v110
	s_cbranch_vccnz .LBB0_486
.LBB0_719:
	v_mov_b32_e32 v111, v110
	v_mov_b32_e32 v250, v110
	s_nop 1
	v_permlane32_swap_b32_e32 v111, v250
	v_cndmask_b32_e64 v111, v111, v250, s[10:11]
	s_waitcnt vmcnt(1) lgkmcnt(0)
	v_mul_f32_e32 v111, v79, v111
	v_cndmask_b32_e64 v111, v111, -v111, s[10:11]
	v_fmac_f32_e32 v111, v110, v78
	v_mov_b32_e32 v110, v111
	v_mul_f32_e32 v111, v61, v109
	s_and_b64 vcc, exec, s[0:1]
	v_mul_f32_e32 v111, v29, v111
	s_cbranch_vccnz .LBB0_487
.LBB0_720:
	v_mov_b32_e32 v112, v111
	v_mov_b32_e32 v250, v111
	s_nop 1
	v_permlane32_swap_b32_e32 v112, v250
	v_cndmask_b32_e64 v112, v112, v250, s[10:11]
	s_waitcnt vmcnt(1) lgkmcnt(0)
	v_mul_f32_e32 v112, v81, v112
	v_cndmask_b32_e64 v112, v112, -v112, s[10:11]
	v_fmac_f32_e32 v112, v111, v80
	v_mov_b32_e32 v111, v112
	v_mul_f32_e32 v112, v54, v109
	s_and_b64 vcc, exec, s[0:1]
	v_mul_f32_e32 v112, v22, v112
	s_cbranch_vccnz .LBB0_488
.LBB0_721:
	v_mov_b32_e32 v113, v112
	v_mov_b32_e32 v250, v112
	s_nop 1
	v_permlane32_swap_b32_e32 v113, v250
	v_cndmask_b32_e64 v113, v113, v250, s[10:11]
	s_waitcnt vmcnt(2) lgkmcnt(0)
	v_mul_f32_e32 v113, v75, v113
	v_cndmask_b32_e64 v113, v113, -v113, s[10:11]
	v_fmac_f32_e32 v113, v112, v74
	v_mov_b32_e32 v112, v113
	v_mul_f32_e32 v113, v55, v109
	s_and_b64 vcc, exec, s[0:1]
	v_mul_f32_e32 v113, v23, v113
	s_cbranch_vccnz .LBB0_489
.LBB0_722:
	v_mov_b32_e32 v114, v113
	v_mov_b32_e32 v250, v113
	s_nop 1
	v_permlane32_swap_b32_e32 v114, v250
	v_cndmask_b32_e64 v114, v114, v250, s[10:11]
	s_waitcnt vmcnt(2) lgkmcnt(0)
	v_mul_f32_e32 v114, v77, v114
	v_cndmask_b32_e64 v114, v114, -v114, s[10:11]
	v_fmac_f32_e32 v114, v113, v76
	v_mov_b32_e32 v113, v114
	v_mul_f32_e32 v114, v56, v109
	s_and_b64 vcc, exec, s[0:1]
	v_mul_f32_e32 v114, v24, v114
	s_cbranch_vccnz .LBB0_490
.LBB0_723:
	v_mov_b32_e32 v115, v114
	v_mov_b32_e32 v250, v114
	s_nop 1
	v_permlane32_swap_b32_e32 v115, v250
	v_cndmask_b32_e64 v115, v115, v250, s[10:11]
	s_waitcnt vmcnt(3) lgkmcnt(0)
	v_mul_f32_e32 v115, v71, v115
	v_cndmask_b32_e64 v115, v115, -v115, s[10:11]
	v_fmac_f32_e32 v115, v114, v70
	v_mov_b32_e32 v114, v115
	v_mul_f32_e32 v109, v57, v109
	s_and_b64 vcc, exec, s[0:1]
	v_mul_f32_e32 v116, v25, v109
	s_cbranch_vccz .LBB0_491
	s_branch .LBB0_492

.LBB0_729:
	v_mov_b32_e32 v87, v0
	v_mov_b32_e32 v250, v0
	s_nop 1
	v_permlane32_swap_b32_e32 v87, v250
	v_cndmask_b32_e64 v87, v87, v250, s[10:11]
	s_waitcnt vmcnt(0) lgkmcnt(0)
	v_mul_f32_e32 v87, v67, v87
	v_cndmask_b32_e64 v87, v87, -v87, s[10:11]
	v_fmac_f32_e32 v87, v0, v66
	v_mov_b32_e32 v0, v87
	v_mul_f32_e32 v87, v51, v93
	s_and_b64 vcc, exec, s[0:1]
	v_mul_f32_e32 v87, v39, v87
	s_cbranch_vccnz .LBB0_518
.LBB0_730:
	v_mov_b32_e32 v88, v87
	v_mov_b32_e32 v250, v87
	s_nop 1
	v_permlane32_swap_b32_e32 v88, v250
	v_cndmask_b32_e64 v88, v88, v250, s[10:11]
	s_waitcnt vmcnt(0) lgkmcnt(0)
	v_mul_f32_e32 v88, v69, v88
	v_cndmask_b32_e64 v88, v88, -v88, s[10:11]
	v_fmac_f32_e32 v88, v87, v68
	v_mov_b32_e32 v87, v88
	v_mul_f32_e32 v88, v52, v93
	s_and_b64 vcc, exec, s[0:1]
	v_mul_f32_e32 v88, v40, v88
	s_cbranch_vccnz .LBB0_519
.LBB0_731:
	v_mov_b32_e32 v89, v88
	v_mov_b32_e32 v250, v88
	s_nop 1
	v_permlane32_swap_b32_e32 v89, v250
	v_cndmask_b32_e64 v89, v89, v250, s[10:11]
	s_waitcnt vmcnt(1) lgkmcnt(0)
	v_mul_f32_e32 v89, v63, v89
	v_cndmask_b32_e64 v89, v89, -v89, s[10:11]
	v_fmac_f32_e32 v89, v88, v62
	v_mov_b32_e32 v88, v89
	v_mul_f32_e32 v89, v53, v93
	s_and_b64 vcc, exec, s[0:1]
	v_mul_f32_e32 v89, v41, v89
	s_cbranch_vccnz .LBB0_520
.LBB0_732:
	v_mov_b32_e32 v90, v89
	v_mov_b32_e32 v250, v89
	s_nop 1
	v_permlane32_swap_b32_e32 v90, v250
	v_cndmask_b32_e64 v90, v90, v250, s[10:11]
	s_waitcnt vmcnt(1) lgkmcnt(0)
	v_mul_f32_e32 v90, v65, v90
	v_cndmask_b32_e64 v90, v90, -v90, s[10:11]
	v_fmac_f32_e32 v90, v89, v64
	v_mov_b32_e32 v89, v90
	v_mul_f32_e32 v90, v46, v93
	s_and_b64 vcc, exec, s[0:1]
	v_mul_f32_e32 v90, v34, v90
	s_cbranch_vccnz .LBB0_521
.LBB0_733:
	v_mov_b32_e32 v91, v90
	v_mov_b32_e32 v250, v90
	s_nop 1
	v_permlane32_swap_b32_e32 v91, v250
	v_cndmask_b32_e64 v91, v91, v250, s[10:11]
	s_waitcnt vmcnt(2) lgkmcnt(0)
	v_mul_f32_e32 v91, v59, v91
	v_cndmask_b32_e64 v91, v91, -v91, s[10:11]
	v_fmac_f32_e32 v91, v90, v58
	v_mov_b32_e32 v90, v91
	v_mul_f32_e32 v91, v47, v93
	s_and_b64 vcc, exec, s[0:1]
	v_mul_f32_e32 v91, v35, v91
	s_cbranch_vccnz .LBB0_522
.LBB0_734:
	v_mov_b32_e32 v94, v91
	v_mov_b32_e32 v250, v91
	s_nop 1
	v_permlane32_swap_b32_e32 v94, v250
	v_cndmask_b32_e64 v94, v94, v250, s[10:11]
	s_waitcnt vmcnt(2) lgkmcnt(0)
	v_mul_f32_e32 v94, v61, v94
	v_cndmask_b32_e64 v94, v94, -v94, s[10:11]
	v_fmac_f32_e32 v94, v91, v60
	v_mov_b32_e32 v91, v94
	v_mul_f32_e32 v94, v48, v93
	s_and_b64 vcc, exec, s[0:1]
	v_mul_f32_e32 v94, v36, v94
	s_cbranch_vccnz .LBB0_523
.LBB0_735:
	v_mov_b32_e32 v95, v94
	v_mov_b32_e32 v250, v94
	s_nop 1
	v_permlane32_swap_b32_e32 v95, v250
	v_cndmask_b32_e64 v95, v95, v250, s[10:11]
	s_waitcnt vmcnt(3) lgkmcnt(0)
	v_mul_f32_e32 v95, v55, v95
	v_cndmask_b32_e64 v95, v95, -v95, s[10:11]
	v_fmac_f32_e32 v95, v94, v54
	v_mov_b32_e32 v94, v95
	v_mul_f32_e32 v95, v49, v93
	s_and_b64 vcc, exec, s[0:1]
	v_mul_f32_e32 v99, v37, v95
	s_cbranch_vccz .LBB0_524
	s_branch .LBB0_525

.LBB0_738:
	v_mov_b32_e32 v90, v0
	v_mov_b32_e32 v250, v0
	s_nop 1
	v_permlane32_swap_b32_e32 v90, v250
	v_cndmask_b32_e64 v90, v90, v250, s[10:11]
	s_waitcnt vmcnt(0) lgkmcnt(0)
	v_mul_f32_e32 v90, v67, v90
	v_cndmask_b32_e64 v90, v90, -v90, s[10:11]
	v_fmac_f32_e32 v90, v0, v66
	v_mov_b32_e32 v0, v90
	v_mul_f32_e32 v90, v43, v93
	s_and_b64 vcc, exec, s[0:1]
	v_mul_f32_e32 v90, v27, v90
	s_cbranch_vccnz .LBB0_531
.LBB0_739:
	v_mov_b32_e32 v94, v90
	v_mov_b32_e32 v250, v90
	s_nop 1
	v_permlane32_swap_b32_e32 v94, v250
	v_cndmask_b32_e64 v94, v94, v250, s[10:11]
	s_waitcnt vmcnt(0) lgkmcnt(0)
	v_mul_f32_e32 v94, v69, v94
	v_cndmask_b32_e64 v94, v94, -v94, s[10:11]
	v_fmac_f32_e32 v94, v90, v68
	v_mov_b32_e32 v90, v94
	v_mul_f32_e32 v94, v44, v93
	s_and_b64 vcc, exec, s[0:1]
	v_mul_f32_e32 v94, v28, v94
	s_cbranch_vccnz .LBB0_532
.LBB0_740:
	v_mov_b32_e32 v95, v94
	v_mov_b32_e32 v250, v94
	s_nop 1
	v_permlane32_swap_b32_e32 v95, v250
	v_cndmask_b32_e64 v95, v95, v250, s[10:11]
	s_waitcnt vmcnt(1) lgkmcnt(0)
	v_mul_f32_e32 v95, v63, v95
	v_cndmask_b32_e64 v95, v95, -v95, s[10:11]
	v_fmac_f32_e32 v95, v94, v62
	v_mov_b32_e32 v94, v95
	v_mul_f32_e32 v95, v45, v93
	s_and_b64 vcc, exec, s[0:1]
	v_mul_f32_e32 v95, v29, v95
	s_cbranch_vccnz .LBB0_533
.LBB0_741:
	v_mov_b32_e32 v96, v95
	v_mov_b32_e32 v250, v95
	s_nop 1
	v_permlane32_swap_b32_e32 v96, v250
	v_cndmask_b32_e64 v96, v96, v250, s[10:11]
	s_waitcnt vmcnt(1) lgkmcnt(0)
	v_mul_f32_e32 v96, v65, v96
	v_cndmask_b32_e64 v96, v96, -v96, s[10:11]
	v_fmac_f32_e32 v96, v95, v64
	v_mov_b32_e32 v95, v96
	v_mul_f32_e32 v96, v30, v93
	s_and_b64 vcc, exec, s[0:1]
	v_mul_f32_e32 v96, v22, v96
	s_cbranch_vccnz .LBB0_534
.LBB0_742:
	v_mov_b32_e32 v97, v96
	v_mov_b32_e32 v250, v96
	s_nop 1
	v_permlane32_swap_b32_e32 v97, v250
	v_cndmask_b32_e64 v97, v97, v250, s[10:11]
	s_waitcnt vmcnt(2) lgkmcnt(0)
	v_mul_f32_e32 v97, v59, v97
	v_cndmask_b32_e64 v97, v97, -v97, s[10:11]
	v_fmac_f32_e32 v97, v96, v58
	v_mov_b32_e32 v96, v97
	v_mul_f32_e32 v97, v31, v93
	s_and_b64 vcc, exec, s[0:1]
	v_mul_f32_e32 v97, v23, v97
	s_cbranch_vccnz .LBB0_535
.LBB0_743:
	v_mov_b32_e32 v98, v97
	v_mov_b32_e32 v250, v97
	s_nop 1
	v_permlane32_swap_b32_e32 v98, v250
	v_cndmask_b32_e64 v98, v98, v250, s[10:11]
	s_waitcnt vmcnt(2) lgkmcnt(0)
	v_mul_f32_e32 v98, v61, v98
	v_cndmask_b32_e64 v98, v98, -v98, s[10:11]
	v_fmac_f32_e32 v98, v97, v60
	v_mov_b32_e32 v97, v98
	v_mul_f32_e32 v98, v32, v93
	s_and_b64 vcc, exec, s[0:1]
	v_mul_f32_e32 v98, v24, v98
	s_cbranch_vccnz .LBB0_536
.LBB0_744:
	v_mov_b32_e32 v99, v98
	v_mov_b32_e32 v250, v98
	s_nop 1
	v_permlane32_swap_b32_e32 v99, v250
	v_cndmask_b32_e64 v99, v99, v250, s[10:11]
	s_waitcnt vmcnt(3) lgkmcnt(0)
	v_mul_f32_e32 v99, v55, v99
	v_cndmask_b32_e64 v99, v99, -v99, s[10:11]
	v_fmac_f32_e32 v99, v98, v54
	v_mov_b32_e32 v98, v99
	v_mul_f32_e32 v93, v33, v93
	s_and_b64 vcc, exec, s[0:1]
	v_mul_f32_e32 v100, v25, v93
	s_cbranch_vccz .LBB0_537
	s_branch .LBB0_538

.LBB0_750:
	v_mov_b32_e32 v31, v0
	v_mov_b32_e32 v250, v0
	s_nop 1
	v_permlane32_swap_b32_e32 v31, v250
	v_cndmask_b32_e64 v31, v31, v250, s[10:11]
	s_waitcnt vmcnt(0) lgkmcnt(0)
	v_mul_f32_e32 v31, v67, v31
	v_cndmask_b32_e64 v31, v31, -v31, s[10:11]
	v_fmac_f32_e32 v31, v0, v66
	v_mov_b32_e32 v0, v31
	v_mul_f32_e32 v31, v19, v43
	s_and_b64 vcc, exec, s[0:1]
	v_mul_f32_e32 v31, v39, v31
	s_cbranch_vccnz .LBB0_569
.LBB0_751:
	v_mov_b32_e32 v32, v31
	v_mov_b32_e32 v250, v31
	s_nop 1
	v_permlane32_swap_b32_e32 v32, v250
	v_cndmask_b32_e64 v32, v32, v250, s[10:11]
	s_waitcnt vmcnt(0) lgkmcnt(0)
	v_mul_f32_e32 v32, v69, v32
	v_cndmask_b32_e64 v32, v32, -v32, s[10:11]
	v_fmac_f32_e32 v32, v31, v68
	v_mov_b32_e32 v31, v32
	v_mul_f32_e32 v32, v20, v43
	s_and_b64 vcc, exec, s[0:1]
	v_mul_f32_e32 v32, v40, v32
	s_cbranch_vccnz .LBB0_570
.LBB0_752:
	v_mov_b32_e32 v33, v32
	v_mov_b32_e32 v250, v32
	s_nop 1
	v_permlane32_swap_b32_e32 v33, v250
	v_cndmask_b32_e64 v33, v33, v250, s[10:11]
	s_waitcnt vmcnt(1) lgkmcnt(0)
	v_mul_f32_e32 v33, v63, v33
	v_cndmask_b32_e64 v33, v33, -v33, s[10:11]
	v_fmac_f32_e32 v33, v32, v62
	v_mov_b32_e32 v32, v33
	v_mul_f32_e32 v33, v21, v43
	s_and_b64 vcc, exec, s[0:1]
	v_mul_f32_e32 v33, v41, v33
	s_cbranch_vccnz .LBB0_571
.LBB0_753:
	v_mov_b32_e32 v38, v33
	v_mov_b32_e32 v250, v33
	s_nop 1
	v_permlane32_swap_b32_e32 v38, v250
	v_cndmask_b32_e64 v38, v38, v250, s[10:11]
	s_waitcnt vmcnt(1) lgkmcnt(0)
	v_mul_f32_e32 v38, v65, v38
	v_cndmask_b32_e64 v38, v38, -v38, s[10:11]
	v_fmac_f32_e32 v38, v33, v64
	v_mov_b32_e32 v33, v38
	v_mul_f32_e32 v38, v14, v43
	s_and_b64 vcc, exec, s[0:1]
	v_mul_f32_e32 v34, v34, v38
	s_cbranch_vccnz .LBB0_572
.LBB0_754:
	v_mov_b32_e32 v38, v34
	v_mov_b32_e32 v250, v34
	s_nop 1
	v_permlane32_swap_b32_e32 v38, v250
	v_cndmask_b32_e64 v38, v38, v250, s[10:11]
	s_waitcnt vmcnt(2) lgkmcnt(0)
	v_mul_f32_e32 v38, v59, v38
	v_cndmask_b32_e64 v38, v38, -v38, s[10:11]
	v_fmac_f32_e32 v38, v34, v58
	v_mov_b32_e32 v34, v38
	v_mul_f32_e32 v38, v15, v43
	s_and_b64 vcc, exec, s[0:1]
	v_mul_f32_e32 v35, v35, v38
	s_cbranch_vccnz .LBB0_573
.LBB0_755:
	v_mov_b32_e32 v38, v35
	v_mov_b32_e32 v250, v35
	s_nop 1
	v_permlane32_swap_b32_e32 v38, v250
	v_cndmask_b32_e64 v38, v38, v250, s[10:11]
	s_waitcnt vmcnt(2) lgkmcnt(0)
	v_mul_f32_e32 v38, v61, v38
	v_cndmask_b32_e64 v38, v38, -v38, s[10:11]
	v_fmac_f32_e32 v38, v35, v60
	v_mov_b32_e32 v35, v38
	v_mul_f32_e32 v38, v16, v43
	s_and_b64 vcc, exec, s[0:1]
	v_mul_f32_e32 v36, v36, v38
	s_cbranch_vccnz .LBB0_574
.LBB0_756:
	v_mov_b32_e32 v38, v36
	v_mov_b32_e32 v250, v36
	s_nop 1
	v_permlane32_swap_b32_e32 v38, v250
	v_cndmask_b32_e64 v38, v38, v250, s[10:11]
	s_waitcnt vmcnt(3) lgkmcnt(0)
	v_mul_f32_e32 v38, v55, v38
	v_cndmask_b32_e64 v38, v38, -v38, s[10:11]
	v_fmac_f32_e32 v38, v36, v54
	v_mov_b32_e32 v36, v38
	v_mul_f32_e32 v38, v17, v43
	s_and_b64 vcc, exec, s[0:1]
	v_mul_f32_e32 v41, v37, v38
	s_cbranch_vccz .LBB0_575
	s_branch .LBB0_576

.LBB0_759:
	v_mov_b32_e32 v34, v26
	v_mov_b32_e32 v250, v26
	s_nop 1
	v_permlane32_swap_b32_e32 v34, v250
	v_cndmask_b32_e64 v34, v34, v250, s[10:11]
	s_waitcnt vmcnt(0) lgkmcnt(0)
	v_mul_f32_e32 v34, v67, v34
	v_cndmask_b32_e64 v34, v34, -v34, s[10:11]
	v_fmac_f32_e32 v34, v26, v66
	v_mov_b32_e32 v26, v34
	v_mul_f32_e32 v34, v11, v43
	s_and_b64 vcc, exec, s[0:1]
	v_mul_f32_e32 v27, v27, v34
	s_cbranch_vccnz .LBB0_582
.LBB0_760:
	v_mov_b32_e32 v34, v27
	v_mov_b32_e32 v250, v27
	s_nop 1
	v_permlane32_swap_b32_e32 v34, v250
	v_cndmask_b32_e64 v34, v34, v250, s[10:11]
	s_waitcnt vmcnt(0) lgkmcnt(0)
	v_mul_f32_e32 v34, v69, v34
	v_cndmask_b32_e64 v34, v34, -v34, s[10:11]
	v_fmac_f32_e32 v34, v27, v68
	v_mov_b32_e32 v27, v34
	v_mul_f32_e32 v34, v12, v43
	s_and_b64 vcc, exec, s[0:1]
	v_mul_f32_e32 v28, v28, v34
	s_cbranch_vccnz .LBB0_583
.LBB0_761:
	v_mov_b32_e32 v34, v28
	v_mov_b32_e32 v250, v28
	s_nop 1
	v_permlane32_swap_b32_e32 v34, v250
	v_cndmask_b32_e64 v34, v34, v250, s[10:11]
	s_waitcnt vmcnt(1) lgkmcnt(0)
	v_mul_f32_e32 v34, v63, v34
	v_cndmask_b32_e64 v34, v34, -v34, s[10:11]
	v_fmac_f32_e32 v34, v28, v62
	v_mov_b32_e32 v28, v34
	v_mul_f32_e32 v34, v13, v43
	s_and_b64 vcc, exec, s[0:1]
	v_mul_f32_e32 v29, v29, v34
	s_cbranch_vccnz .LBB0_584
.LBB0_762:
	v_mov_b32_e32 v34, v29
	v_mov_b32_e32 v250, v29
	s_nop 1
	v_permlane32_swap_b32_e32 v34, v250
	v_cndmask_b32_e64 v34, v34, v250, s[10:11]
	s_waitcnt vmcnt(1) lgkmcnt(0)
	v_mul_f32_e32 v34, v65, v34
	v_cndmask_b32_e64 v34, v34, -v34, s[10:11]
	v_fmac_f32_e32 v34, v29, v64
	v_mov_b32_e32 v29, v34
	v_mul_f32_e32 v34, v6, v43
	s_and_b64 vcc, exec, s[0:1]
	v_mul_f32_e32 v22, v22, v34
	s_cbranch_vccnz .LBB0_585
.LBB0_763:
	v_mov_b32_e32 v34, v22
	v_mov_b32_e32 v250, v22
	s_nop 1
	v_permlane32_swap_b32_e32 v34, v250
	v_cndmask_b32_e64 v34, v34, v250, s[10:11]
	s_waitcnt vmcnt(2) lgkmcnt(0)
	v_mul_f32_e32 v34, v59, v34
	v_cndmask_b32_e64 v34, v34, -v34, s[10:11]
	v_fmac_f32_e32 v34, v22, v58
	v_mov_b32_e32 v22, v34
	v_mul_f32_e32 v34, v7, v43
	s_and_b64 vcc, exec, s[0:1]
	v_mul_f32_e32 v34, v23, v34
	s_cbranch_vccnz .LBB0_586
.LBB0_764:
	v_mov_b32_e32 v23, v34
	v_mov_b32_e32 v250, v34
	s_nop 1
	v_permlane32_swap_b32_e32 v23, v250
	v_cndmask_b32_e64 v23, v23, v250, s[10:11]
	s_waitcnt vmcnt(2) lgkmcnt(0)
	v_mul_f32_e32 v23, v61, v23
	v_cndmask_b32_e64 v23, v23, -v23, s[10:11]
	v_fmac_f32_e32 v23, v34, v60
	v_mov_b32_e32 v34, v23
	v_mul_f32_e32 v23, v8, v43
	s_and_b64 vcc, exec, s[0:1]
	v_mul_f32_e32 v23, v24, v23
	s_cbranch_vccnz .LBB0_587
.LBB0_765:
	v_mov_b32_e32 v24, v23
	v_mov_b32_e32 v250, v23
	s_nop 1
	v_permlane32_swap_b32_e32 v24, v250
	v_cndmask_b32_e64 v24, v24, v250, s[10:11]
	s_waitcnt vmcnt(3) lgkmcnt(0)
	v_mul_f32_e32 v24, v55, v24
	v_cndmask_b32_e64 v24, v24, -v24, s[10:11]
	v_fmac_f32_e32 v24, v23, v54
	v_mov_b32_e32 v23, v24
	v_mul_f32_e32 v24, v9, v43
	s_and_b64 vcc, exec, s[0:1]
	v_mul_f32_e32 v25, v25, v24
	s_cbranch_vccz .LBB0_588
	s_branch .LBB0_589
